# speedup vs baseline: 1.0154x; 1.0031x over previous
.LBB0_1901:
	s_add_u32 s10, s14, s0
	s_addc_u32 s11, s15, s1
	v_lshl_add_u64 v[30:31], s[14:15], 0, v[4:5]
	global_load_dwordx4 v[10:13], v0, s[10:11]
	global_load_dwordx2 v[32:33], v[30:31], off offset:-1024
	s_add_u32 s10, s10, 0x500000
	s_addc_u32 s11, s11, 0
	global_load_dwordx4 v[14:17], v1, s[10:11] offset:16
	global_load_dwordx4 v[18:21], v1, s[10:11] offset:32
	global_load_dwordx4 v[22:25], v1, s[10:11] offset:48
	global_load_dwordx2 v[36:37], v[30:31], off offset:-512
	global_load_dwordx2 v[38:39], v[30:31], off
	global_load_dwordx2 v[56:57], v[30:31], off offset:512
	s_add_i32 s8, s8, s34
	s_add_u32 s0, s0, s2
	s_addc_u32 s1, s1, s3
	v_lshl_add_u64 v[4:5], v[4:5], 0, s[4:5]
	s_cmpk_gt_i32 s8, 0x3fff
	s_waitcnt vmcnt(7)
	v_mov_b32_e32 v34, v11
	v_mov_b32_e32 v35, v12
	v_mov_b32_e32 v11, v13
	v_pk_add_f32 v[10:11], v[34:35], v[10:11]
	s_waitcnt vmcnt(6)
	v_lshlrev_b32_e32 v12, 16, v32
	v_add_f32_e32 v9, v10, v11
	s_waitcnt vmcnt(5)
	v_mov_b32_e32 v10, v15
	v_mov_b32_e32 v11, v16
	v_mov_b32_e32 v15, v17
	v_pk_add_f32 v[10:11], v[10:11], v[14:15]
	s_waitcnt vmcnt(4)
	v_add_f32_e32 v16, v18, v19
	v_pk_add_f32 v[10:11], v[10:11], v[10:11] op_sel:[0,1] op_sel_hi:[1,0]
	v_add_f32_e32 v18, v20, v21
	s_waitcnt vmcnt(3)
	v_mov_b32_e32 v21, v22
	v_mov_b32_e32 v17, v24
	v_mov_b32_e32 v19, v25
	v_add_f32_e32 v20, 0, v9
	v_mov_b32_e32 v11, v23
	v_pk_add_f32 v[14:15], v[16:17], v[18:19]
	v_pk_add_f32 v[10:11], v[20:21], v[10:11]
	v_and_b32_e32 v13, 0xffff0000, v32
	v_pk_add_f32 v[10:11], v[10:11], v[14:15]
	v_lshlrev_b32_e32 v32, 16, v33
	v_add_f32_e32 v9, v10, v11
	v_fmamk_f32 v9, v9, 0x3a800000, v8
	v_mul_f32_e32 v10, 0x4b800000, v9
	v_cmp_gt_f32_e32 vcc, s9, v9
	v_and_b32_e32 v33, 0xffff0000, v33
	s_nop 0
	v_cndmask_b32_e32 v9, v9, v10, vcc
	v_rsq_f32_e32 v9, v9
	s_nop 0
	v_mul_f32_e32 v10, 0x45800000, v9
	v_cndmask_b32_e32 v14, v9, v10, vcc
	v_pk_mul_f32 v[10:11], v[14:15], v[12:13] op_sel_hi:[0,1]
	v_pk_mul_f32 v[12:13], v[14:15], v[32:33] op_sel_hi:[0,1]
	v_pk_mul_f32 v[12:13], v[42:43], v[12:13]
	v_pk_mul_f32 v[10:11], v[40:41], v[10:11]
	global_store_dwordx4 v[6:7], v[10:13], off offset:-3072 sc0 sc1
	s_waitcnt vmcnt(3)
	v_mov_b64_e32 v[16:17], v[36:37]
	v_mov_b64_e32 v[10:11], v[44:45]
	v_mov_b64_e32 v[12:13], v[46:47]
	v_lshlrev_b32_e32 v18, 16, v16
	v_and_b32_e32 v19, 0xffff0000, v16
	v_lshlrev_b32_e32 v16, 16, v17
	v_and_b32_e32 v17, 0xffff0000, v17
	v_pk_mul_f32 v[18:19], v[14:15], v[18:19] op_sel_hi:[0,1]
	v_pk_mul_f32 v[16:17], v[14:15], v[16:17] op_sel_hi:[0,1]
	v_pk_mul_f32 v[12:13], v[12:13], v[16:17]
	v_pk_mul_f32 v[10:11], v[10:11], v[18:19]
	global_store_dwordx4 v[6:7], v[10:13], off offset:-2048 sc0 sc1
	s_waitcnt vmcnt(3)
	v_mov_b64_e32 v[16:17], v[38:39]
	v_mov_b64_e32 v[10:11], v[48:49]
	v_mov_b64_e32 v[12:13], v[50:51]
	v_lshlrev_b32_e32 v18, 16, v16
	v_and_b32_e32 v19, 0xffff0000, v16
	v_lshlrev_b32_e32 v16, 16, v17
	v_and_b32_e32 v17, 0xffff0000, v17
	v_pk_mul_f32 v[18:19], v[14:15], v[18:19] op_sel_hi:[0,1]
	v_pk_mul_f32 v[16:17], v[14:15], v[16:17] op_sel_hi:[0,1]
	v_pk_mul_f32 v[12:13], v[12:13], v[16:17]
	v_pk_mul_f32 v[10:11], v[10:11], v[18:19]
	global_store_dwordx4 v[6:7], v[10:13], off offset:-1024 sc0 sc1
	s_waitcnt vmcnt(3)
	v_mov_b64_e32 v[16:17], v[56:57]
	v_mov_b64_e32 v[10:11], v[52:53]
	v_mov_b64_e32 v[12:13], v[54:55]
	v_lshlrev_b32_e32 v18, 16, v16
	v_and_b32_e32 v19, 0xffff0000, v16
	v_lshlrev_b32_e32 v16, 16, v17
	v_and_b32_e32 v17, 0xffff0000, v17
	v_pk_mul_f32 v[18:19], v[14:15], v[18:19] op_sel_hi:[0,1]
	v_pk_mul_f32 v[14:15], v[14:15], v[16:17] op_sel_hi:[0,1]
	v_pk_mul_f32 v[12:13], v[12:13], v[14:15]
	v_pk_mul_f32 v[10:11], v[10:11], v[18:19]
	global_store_dwordx4 v[6:7], v[10:13], off sc0 sc1
	v_lshl_add_u64 v[6:7], v[6:7], 0, s[6:7]
	s_cbranch_scc0 .LBB0_1901
